# P7 256-tile SwiGLU epilogue rewritten by hand: packed f32 mul/add on row pairs, rstd quads read up front, one bf16 pack per row pair with d16_hi stores, SGPR-base store addressing (same f32 math)
# speedup vs baseline: 1.0216x; 1.0144x over previous
; DI float fexp2(float x) { return __builtin_amdgcn_exp2f(x); }
;     ...
;   if constexpr (EPI == EPI_GU) {
;     __syncthreads();
;     const float* rstdL = (const float*)(smem + SMEM_RSTD);
; #pragma unroll
;     for (int ai = 0; ai < 2; ++ai)
; #pragma unroll
;       for (int m = 0; m < 4; ++m) {
;         const int rowb = ai * 128 + wr * 64 + m * 16 + fq * 4;
;         const f32x4 rs4 = *(const f32x4*)(rstdL + rowb);
; #pragma unroll
;         for (int bj = 0; bj < 2; ++bj) {
;           bf16_t* op = e.out + (size_t)(m0 + rowb) * e.ldo + ((n0 + bj * 128 + wc * 32) >> 1) + fr;
; #pragma unroll
;           for (int j = 0; j < 4; ++j) {
;             const float g = acc[ai][bj][m][0][j] * rs4[j], u = acc[ai][bj][m][1][j] * rs4[j];
;             const float rv = g * __builtin_amdgcn_rcpf(1.f + fexp2(-g * LOG2E)) * u;
;             op[(size_t)j * e.ldo] = (bf16_t)(pack2(rv, 0.f) & 0xffffu);
;           }
;         }
;       }
;     __syncthreads();
;     return;
;   }
.LBB0_1243:
	s_or_b64 exec, exec, s[2:3]
	v_lshl_or_b32 v135, v148, 2, v149
	v_mov_b32_e32 v144, 0x21010
	v_lshl_add_u32 v134, v135, 2, v144
	s_waitcnt vmcnt(8) lgkmcnt(0)
	s_barrier
	ds_read_b128 v[150:153], v134
	ds_read_b128 v[154:157], v134 offset:64
	ds_read_b128 v[158:161], v134 offset:128
	ds_read_b128 v[162:165], v134 offset:192
	ds_read_b128 v[166:169], v134 offset:512
	ds_read_b128 v[170:173], v134 offset:576
	ds_read_b128 v[174:177], v134 offset:640
	ds_read_b128 v[178:181], v134 offset:704
	s_movk_i32 s13, 0x1600
	v_add_u32_e32 v190, s27, v135
	v_mul_lo_u32 v190, v190, s13
	v_lshl_or_b32 v191, v146, 5, s0
	v_ashrrev_i32_e32 v191, 1, v191
	v_add_u32_e32 v191, v191, v147
	v_lshl_add_u32 v190, v191, 1, v190
	s_mov_b32 s12, 0xbfb8aa3b
	s_waitcnt lgkmcnt(7)
	v_pk_mul_f32 v[128:129], v[128:129], v[150:151]
	v_pk_mul_f32 v[130:131], v[130:131], v[152:153]
	v_pk_mul_f32 v[120:121], v[120:121], v[150:151]
	v_pk_mul_f32 v[122:123], v[122:123], v[152:153]
	v_pk_mul_f32 v[182:183], v[128:129], s[12:13] op_sel_hi:[1,0]
	v_pk_mul_f32 v[184:185], v[130:131], s[12:13] op_sel_hi:[1,0]
	v_pk_mul_f32 v[186:187], v[120:121], s[12:13] op_sel_hi:[1,0]
	v_pk_mul_f32 v[188:189], v[122:123], s[12:13] op_sel_hi:[1,0]
	v_exp_f32_e32 v182, v182
	v_exp_f32_e32 v183, v183
	v_exp_f32_e32 v184, v184
	v_exp_f32_e32 v185, v185
	v_exp_f32_e32 v186, v186
	v_exp_f32_e32 v187, v187
	v_exp_f32_e32 v188, v188
	v_exp_f32_e32 v189, v189
	v_mov_b32_e32 v192, v190
	v_add_u32_e32 v193, 0x1000, v192
	v_add_u32_e32 v194, 0x2000, v192
	v_add_u32_e32 v195, 0x4000, v192
	v_pk_add_f32 v[182:183], v[182:183], 1.0 op_sel_hi:[1,0]
	v_pk_add_f32 v[184:185], v[184:185], 1.0 op_sel_hi:[1,0]
	v_pk_add_f32 v[186:187], v[186:187], 1.0 op_sel_hi:[1,0]
	v_pk_add_f32 v[188:189], v[188:189], 1.0 op_sel_hi:[1,0]
	v_rcp_f32_e32 v182, v182
	v_rcp_f32_e32 v183, v183
	v_rcp_f32_e32 v184, v184
	v_rcp_f32_e32 v185, v185
	v_rcp_f32_e32 v186, v186
	v_rcp_f32_e32 v187, v187
	v_rcp_f32_e32 v188, v188
	v_rcp_f32_e32 v189, v189
	v_pk_mul_f32 v[124:125], v[124:125], v[150:151]
	v_pk_mul_f32 v[126:127], v[126:127], v[152:153]
	v_pk_mul_f32 v[116:117], v[116:117], v[150:151]
	v_pk_mul_f32 v[118:119], v[118:119], v[152:153]
	v_pk_mul_f32 v[128:129], v[128:129], v[182:183]
	v_pk_mul_f32 v[130:131], v[130:131], v[184:185]
	v_pk_mul_f32 v[120:121], v[120:121], v[186:187]
	v_pk_mul_f32 v[122:123], v[122:123], v[188:189]
	v_pk_mul_f32 v[124:125], v[124:125], v[128:129]
	v_pk_mul_f32 v[126:127], v[126:127], v[130:131]
	v_pk_mul_f32 v[116:117], v[116:117], v[120:121]
	v_pk_mul_f32 v[118:119], v[118:119], v[122:123]
	v_cvt_pk_bf16_f32 v124, v124, v125
	v_cvt_pk_bf16_f32 v126, v126, v127
	v_cvt_pk_bf16_f32 v116, v116, v117
	v_cvt_pk_bf16_f32 v118, v118, v119
	global_store_short v192, v124, s[30:31]
	global_store_short_d16_hi v193, v124, s[30:31] offset:1536
	global_store_short v194, v126, s[30:31] offset:3072
	global_store_short_d16_hi v195, v126, s[30:31] offset:512
	global_store_short v192, v116, s[30:31] offset:128
	global_store_short_d16_hi v193, v116, s[30:31] offset:1664
	global_store_short v194, v118, s[30:31] offset:3200
	global_store_short_d16_hi v195, v118, s[30:31] offset:640
	s_waitcnt lgkmcnt(6)
	v_pk_mul_f32 v[112:113], v[112:113], v[154:155]
	v_pk_mul_f32 v[114:115], v[114:115], v[156:157]
	v_pk_mul_f32 v[104:105], v[104:105], v[154:155]
	v_pk_mul_f32 v[106:107], v[106:107], v[156:157]
	v_pk_mul_f32 v[182:183], v[112:113], s[12:13] op_sel_hi:[1,0]
	v_pk_mul_f32 v[184:185], v[114:115], s[12:13] op_sel_hi:[1,0]
	v_pk_mul_f32 v[186:187], v[104:105], s[12:13] op_sel_hi:[1,0]
	v_pk_mul_f32 v[188:189], v[106:107], s[12:13] op_sel_hi:[1,0]
	v_exp_f32_e32 v182, v182
	v_exp_f32_e32 v183, v183
	v_exp_f32_e32 v184, v184
	v_exp_f32_e32 v185, v185
	v_exp_f32_e32 v186, v186
	v_exp_f32_e32 v187, v187
	v_exp_f32_e32 v188, v188
	v_exp_f32_e32 v189, v189
	v_add_u32_e32 v192, 0x16000, v190
	v_add_u32_e32 v193, 0x1000, v192
	v_add_u32_e32 v194, 0x2000, v192
	v_add_u32_e32 v195, 0x4000, v192
	v_pk_add_f32 v[182:183], v[182:183], 1.0 op_sel_hi:[1,0]
	v_pk_add_f32 v[184:185], v[184:185], 1.0 op_sel_hi:[1,0]
	v_pk_add_f32 v[186:187], v[186:187], 1.0 op_sel_hi:[1,0]
	v_pk_add_f32 v[188:189], v[188:189], 1.0 op_sel_hi:[1,0]
	v_rcp_f32_e32 v182, v182
	v_rcp_f32_e32 v183, v183
	v_rcp_f32_e32 v184, v184
	v_rcp_f32_e32 v185, v185
	v_rcp_f32_e32 v186, v186
	v_rcp_f32_e32 v187, v187
	v_rcp_f32_e32 v188, v188
	v_rcp_f32_e32 v189, v189
	v_pk_mul_f32 v[108:109], v[108:109], v[154:155]
	v_pk_mul_f32 v[110:111], v[110:111], v[156:157]
	v_pk_mul_f32 v[100:101], v[100:101], v[154:155]
	v_pk_mul_f32 v[102:103], v[102:103], v[156:157]
	v_pk_mul_f32 v[112:113], v[112:113], v[182:183]
	v_pk_mul_f32 v[114:115], v[114:115], v[184:185]
	v_pk_mul_f32 v[104:105], v[104:105], v[186:187]
	v_pk_mul_f32 v[106:107], v[106:107], v[188:189]
	v_pk_mul_f32 v[108:109], v[108:109], v[112:113]
	v_pk_mul_f32 v[110:111], v[110:111], v[114:115]
	v_pk_mul_f32 v[100:101], v[100:101], v[104:105]
	v_pk_mul_f32 v[102:103], v[102:103], v[106:107]
	v_cvt_pk_bf16_f32 v108, v108, v109
	v_cvt_pk_bf16_f32 v110, v110, v111
	v_cvt_pk_bf16_f32 v100, v100, v101
	v_cvt_pk_bf16_f32 v102, v102, v103
	global_store_short v192, v108, s[30:31]
	global_store_short_d16_hi v193, v108, s[30:31] offset:1536
	global_store_short v194, v110, s[30:31] offset:3072
	global_store_short_d16_hi v195, v110, s[30:31] offset:512
	global_store_short v192, v100, s[30:31] offset:128
	global_store_short_d16_hi v193, v100, s[30:31] offset:1664
	global_store_short v194, v102, s[30:31] offset:3200
	global_store_short_d16_hi v195, v102, s[30:31] offset:640
	s_waitcnt lgkmcnt(5)
; DI float fexp2(float x) { return __builtin_amdgcn_exp2f(x); }
;     ...
;       for (int m = 0; m < 4; ++m) {
;         const int rowb = ai * 128 + wr * 64 + m * 16 + fq * 4;
;         const f32x4 rs4 = *(const f32x4*)(rstdL + rowb);
; #pragma unroll
;         for (int bj = 0; bj < 2; ++bj) {
;           bf16_t* op = e.out + (size_t)(m0 + rowb) * e.ldo + ((n0 + bj * 128 + wc * 32) >> 1) + fr;
; #pragma unroll
;           for (int j = 0; j < 4; ++j) {
;             const float g = acc[ai][bj][m][0][j] * rs4[j], u = acc[ai][bj][m][1][j] * rs4[j];
;             const float rv = g * __builtin_amdgcn_rcpf(1.f + fexp2(-g * LOG2E)) * u;
;             op[(size_t)j * e.ldo] = (bf16_t)(pack2(rv, 0.f) & 0xffffu);
;           }
;         }
	v_pk_mul_f32 v[96:97], v[96:97], v[158:159]
	v_pk_mul_f32 v[98:99], v[98:99], v[160:161]
	v_pk_mul_f32 v[88:89], v[88:89], v[158:159]
	v_pk_mul_f32 v[90:91], v[90:91], v[160:161]
	v_pk_mul_f32 v[182:183], v[96:97], s[12:13] op_sel_hi:[1,0]
	v_pk_mul_f32 v[184:185], v[98:99], s[12:13] op_sel_hi:[1,0]
	v_pk_mul_f32 v[186:187], v[88:89], s[12:13] op_sel_hi:[1,0]
	v_pk_mul_f32 v[188:189], v[90:91], s[12:13] op_sel_hi:[1,0]
	v_exp_f32_e32 v182, v182
	v_exp_f32_e32 v183, v183
	v_exp_f32_e32 v184, v184
	v_exp_f32_e32 v185, v185
	v_exp_f32_e32 v186, v186
	v_exp_f32_e32 v187, v187
	v_exp_f32_e32 v188, v188
	v_exp_f32_e32 v189, v189
	v_add_u32_e32 v192, 0x2c000, v190
	v_add_u32_e32 v193, 0x1000, v192
	v_add_u32_e32 v194, 0x2000, v192
	v_add_u32_e32 v195, 0x4000, v192
	v_pk_add_f32 v[182:183], v[182:183], 1.0 op_sel_hi:[1,0]
	v_pk_add_f32 v[184:185], v[184:185], 1.0 op_sel_hi:[1,0]
	v_pk_add_f32 v[186:187], v[186:187], 1.0 op_sel_hi:[1,0]
	v_pk_add_f32 v[188:189], v[188:189], 1.0 op_sel_hi:[1,0]
	v_rcp_f32_e32 v182, v182
	v_rcp_f32_e32 v183, v183
	v_rcp_f32_e32 v184, v184
	v_rcp_f32_e32 v185, v185
	v_rcp_f32_e32 v186, v186
	v_rcp_f32_e32 v187, v187
	v_rcp_f32_e32 v188, v188
	v_rcp_f32_e32 v189, v189
	v_pk_mul_f32 v[92:93], v[92:93], v[158:159]
	v_pk_mul_f32 v[94:95], v[94:95], v[160:161]
	v_pk_mul_f32 v[84:85], v[84:85], v[158:159]
	v_pk_mul_f32 v[86:87], v[86:87], v[160:161]
	v_pk_mul_f32 v[96:97], v[96:97], v[182:183]
	v_pk_mul_f32 v[98:99], v[98:99], v[184:185]
	v_pk_mul_f32 v[88:89], v[88:89], v[186:187]
	v_pk_mul_f32 v[90:91], v[90:91], v[188:189]
	v_pk_mul_f32 v[92:93], v[92:93], v[96:97]
	v_pk_mul_f32 v[94:95], v[94:95], v[98:99]
	v_pk_mul_f32 v[84:85], v[84:85], v[88:89]
	v_pk_mul_f32 v[86:87], v[86:87], v[90:91]
	v_cvt_pk_bf16_f32 v92, v92, v93
	v_cvt_pk_bf16_f32 v94, v94, v95
	v_cvt_pk_bf16_f32 v84, v84, v85
	v_cvt_pk_bf16_f32 v86, v86, v87
	global_store_short v192, v92, s[30:31]
	global_store_short_d16_hi v193, v92, s[30:31] offset:1536
	global_store_short v194, v94, s[30:31] offset:3072
	global_store_short_d16_hi v195, v94, s[30:31] offset:512
	global_store_short v192, v84, s[30:31] offset:128
	global_store_short_d16_hi v193, v84, s[30:31] offset:1664
	global_store_short v194, v86, s[30:31] offset:3200
	global_store_short_d16_hi v195, v86, s[30:31] offset:640
	s_waitcnt lgkmcnt(4)
	v_pk_mul_f32 v[80:81], v[80:81], v[162:163]
	v_pk_mul_f32 v[82:83], v[82:83], v[164:165]
	v_pk_mul_f32 v[72:73], v[72:73], v[162:163]
	v_pk_mul_f32 v[74:75], v[74:75], v[164:165]
	v_pk_mul_f32 v[182:183], v[80:81], s[12:13] op_sel_hi:[1,0]
	v_pk_mul_f32 v[184:185], v[82:83], s[12:13] op_sel_hi:[1,0]
	v_pk_mul_f32 v[186:187], v[72:73], s[12:13] op_sel_hi:[1,0]
	v_pk_mul_f32 v[188:189], v[74:75], s[12:13] op_sel_hi:[1,0]
	v_exp_f32_e32 v182, v182
	v_exp_f32_e32 v183, v183
	v_exp_f32_e32 v184, v184
	v_exp_f32_e32 v185, v185
	v_exp_f32_e32 v186, v186
	v_exp_f32_e32 v187, v187
	v_exp_f32_e32 v188, v188
	v_exp_f32_e32 v189, v189
	v_add_u32_e32 v192, 0x42000, v190
	v_add_u32_e32 v193, 0x1000, v192
	v_add_u32_e32 v194, 0x2000, v192
	v_add_u32_e32 v195, 0x4000, v192
	v_pk_add_f32 v[182:183], v[182:183], 1.0 op_sel_hi:[1,0]
	v_pk_add_f32 v[184:185], v[184:185], 1.0 op_sel_hi:[1,0]
	v_pk_add_f32 v[186:187], v[186:187], 1.0 op_sel_hi:[1,0]
	v_pk_add_f32 v[188:189], v[188:189], 1.0 op_sel_hi:[1,0]
	v_rcp_f32_e32 v182, v182
	v_rcp_f32_e32 v183, v183
	v_rcp_f32_e32 v184, v184
	v_rcp_f32_e32 v185, v185
	v_rcp_f32_e32 v186, v186
	v_rcp_f32_e32 v187, v187
	v_rcp_f32_e32 v188, v188
	v_rcp_f32_e32 v189, v189
	v_pk_mul_f32 v[76:77], v[76:77], v[162:163]
	v_pk_mul_f32 v[78:79], v[78:79], v[164:165]
	v_pk_mul_f32 v[68:69], v[68:69], v[162:163]
	v_pk_mul_f32 v[70:71], v[70:71], v[164:165]
	v_pk_mul_f32 v[80:81], v[80:81], v[182:183]
	v_pk_mul_f32 v[82:83], v[82:83], v[184:185]
	v_pk_mul_f32 v[72:73], v[72:73], v[186:187]
	v_pk_mul_f32 v[74:75], v[74:75], v[188:189]
	v_pk_mul_f32 v[76:77], v[76:77], v[80:81]
	v_pk_mul_f32 v[78:79], v[78:79], v[82:83]
	v_pk_mul_f32 v[68:69], v[68:69], v[72:73]
	v_pk_mul_f32 v[70:71], v[70:71], v[74:75]
	v_cvt_pk_bf16_f32 v76, v76, v77
	v_cvt_pk_bf16_f32 v78, v78, v79
	v_cvt_pk_bf16_f32 v68, v68, v69
	v_cvt_pk_bf16_f32 v70, v70, v71
	global_store_short v192, v76, s[30:31]
	global_store_short_d16_hi v193, v76, s[30:31] offset:1536
	global_store_short v194, v78, s[30:31] offset:3072
	global_store_short_d16_hi v195, v78, s[30:31] offset:512
	global_store_short v192, v68, s[30:31] offset:128
	global_store_short_d16_hi v193, v68, s[30:31] offset:1664
	global_store_short v194, v70, s[30:31] offset:3200
	global_store_short_d16_hi v195, v70, s[30:31] offset:640
	s_waitcnt lgkmcnt(3)
; DI float fexp2(float x) { return __builtin_amdgcn_exp2f(x); }
;     ...
;       for (int m = 0; m < 4; ++m) {
;         const int rowb = ai * 128 + wr * 64 + m * 16 + fq * 4;
;         const f32x4 rs4 = *(const f32x4*)(rstdL + rowb);
; #pragma unroll
;         for (int bj = 0; bj < 2; ++bj) {
;           bf16_t* op = e.out + (size_t)(m0 + rowb) * e.ldo + ((n0 + bj * 128 + wc * 32) >> 1) + fr;
; #pragma unroll
;           for (int j = 0; j < 4; ++j) {
;             const float g = acc[ai][bj][m][0][j] * rs4[j], u = acc[ai][bj][m][1][j] * rs4[j];
;             const float rv = g * __builtin_amdgcn_rcpf(1.f + fexp2(-g * LOG2E)) * u;
;             op[(size_t)j * e.ldo] = (bf16_t)(pack2(rv, 0.f) & 0xffffu);
;           }
;         }
	v_pk_mul_f32 v[64:65], v[64:65], v[166:167]
	v_pk_mul_f32 v[66:67], v[66:67], v[168:169]
	v_pk_mul_f32 v[56:57], v[56:57], v[166:167]
	v_pk_mul_f32 v[58:59], v[58:59], v[168:169]
	v_pk_mul_f32 v[182:183], v[64:65], s[12:13] op_sel_hi:[1,0]
	v_pk_mul_f32 v[184:185], v[66:67], s[12:13] op_sel_hi:[1,0]
	v_pk_mul_f32 v[186:187], v[56:57], s[12:13] op_sel_hi:[1,0]
	v_pk_mul_f32 v[188:189], v[58:59], s[12:13] op_sel_hi:[1,0]
	v_exp_f32_e32 v182, v182
	v_exp_f32_e32 v183, v183
	v_exp_f32_e32 v184, v184
	v_exp_f32_e32 v185, v185
	v_exp_f32_e32 v186, v186
	v_exp_f32_e32 v187, v187
	v_exp_f32_e32 v188, v188
	v_exp_f32_e32 v189, v189
	v_add_u32_e32 v192, 0xb0000, v190
	v_add_u32_e32 v193, 0x1000, v192
	v_add_u32_e32 v194, 0x2000, v192
	v_add_u32_e32 v195, 0x4000, v192
	v_pk_add_f32 v[182:183], v[182:183], 1.0 op_sel_hi:[1,0]
	v_pk_add_f32 v[184:185], v[184:185], 1.0 op_sel_hi:[1,0]
	v_pk_add_f32 v[186:187], v[186:187], 1.0 op_sel_hi:[1,0]
	v_pk_add_f32 v[188:189], v[188:189], 1.0 op_sel_hi:[1,0]
	v_rcp_f32_e32 v182, v182
	v_rcp_f32_e32 v183, v183
	v_rcp_f32_e32 v184, v184
	v_rcp_f32_e32 v185, v185
	v_rcp_f32_e32 v186, v186
	v_rcp_f32_e32 v187, v187
	v_rcp_f32_e32 v188, v188
	v_rcp_f32_e32 v189, v189
	v_pk_mul_f32 v[60:61], v[60:61], v[166:167]
	v_pk_mul_f32 v[62:63], v[62:63], v[168:169]
	v_pk_mul_f32 v[52:53], v[52:53], v[166:167]
	v_pk_mul_f32 v[54:55], v[54:55], v[168:169]
	v_pk_mul_f32 v[64:65], v[64:65], v[182:183]
	v_pk_mul_f32 v[66:67], v[66:67], v[184:185]
	v_pk_mul_f32 v[56:57], v[56:57], v[186:187]
	v_pk_mul_f32 v[58:59], v[58:59], v[188:189]
	v_pk_mul_f32 v[60:61], v[60:61], v[64:65]
	v_pk_mul_f32 v[62:63], v[62:63], v[66:67]
	v_pk_mul_f32 v[52:53], v[52:53], v[56:57]
	v_pk_mul_f32 v[54:55], v[54:55], v[58:59]
	v_cvt_pk_bf16_f32 v60, v60, v61
	v_cvt_pk_bf16_f32 v62, v62, v63
	v_cvt_pk_bf16_f32 v52, v52, v53
	v_cvt_pk_bf16_f32 v54, v54, v55
	global_store_short v192, v60, s[30:31]
	global_store_short_d16_hi v193, v60, s[30:31] offset:1536
	global_store_short v194, v62, s[30:31] offset:3072
	global_store_short_d16_hi v195, v62, s[30:31] offset:512
	global_store_short v192, v52, s[30:31] offset:128
	global_store_short_d16_hi v193, v52, s[30:31] offset:1664
	global_store_short v194, v54, s[30:31] offset:3200
	global_store_short_d16_hi v195, v54, s[30:31] offset:640
	s_waitcnt lgkmcnt(2)
	v_pk_mul_f32 v[48:49], v[48:49], v[170:171]
	v_pk_mul_f32 v[50:51], v[50:51], v[172:173]
	v_pk_mul_f32 v[40:41], v[40:41], v[170:171]
	v_pk_mul_f32 v[42:43], v[42:43], v[172:173]
	v_pk_mul_f32 v[182:183], v[48:49], s[12:13] op_sel_hi:[1,0]
	v_pk_mul_f32 v[184:185], v[50:51], s[12:13] op_sel_hi:[1,0]
	v_pk_mul_f32 v[186:187], v[40:41], s[12:13] op_sel_hi:[1,0]
	v_pk_mul_f32 v[188:189], v[42:43], s[12:13] op_sel_hi:[1,0]
	v_exp_f32_e32 v182, v182
	v_exp_f32_e32 v183, v183
	v_exp_f32_e32 v184, v184
	v_exp_f32_e32 v185, v185
	v_exp_f32_e32 v186, v186
	v_exp_f32_e32 v187, v187
	v_exp_f32_e32 v188, v188
	v_exp_f32_e32 v189, v189
	v_add_u32_e32 v192, 0xc6000, v190
	v_add_u32_e32 v193, 0x1000, v192
	v_add_u32_e32 v194, 0x2000, v192
	v_add_u32_e32 v195, 0x4000, v192
	v_pk_add_f32 v[182:183], v[182:183], 1.0 op_sel_hi:[1,0]
	v_pk_add_f32 v[184:185], v[184:185], 1.0 op_sel_hi:[1,0]
	v_pk_add_f32 v[186:187], v[186:187], 1.0 op_sel_hi:[1,0]
	v_pk_add_f32 v[188:189], v[188:189], 1.0 op_sel_hi:[1,0]
	v_rcp_f32_e32 v182, v182
	v_rcp_f32_e32 v183, v183
	v_rcp_f32_e32 v184, v184
	v_rcp_f32_e32 v185, v185
	v_rcp_f32_e32 v186, v186
	v_rcp_f32_e32 v187, v187
	v_rcp_f32_e32 v188, v188
	v_rcp_f32_e32 v189, v189
	v_pk_mul_f32 v[44:45], v[44:45], v[170:171]
	v_pk_mul_f32 v[46:47], v[46:47], v[172:173]
	v_pk_mul_f32 v[36:37], v[36:37], v[170:171]
	v_pk_mul_f32 v[38:39], v[38:39], v[172:173]
	v_pk_mul_f32 v[48:49], v[48:49], v[182:183]
	v_pk_mul_f32 v[50:51], v[50:51], v[184:185]
	v_pk_mul_f32 v[40:41], v[40:41], v[186:187]
	v_pk_mul_f32 v[42:43], v[42:43], v[188:189]
	v_pk_mul_f32 v[44:45], v[44:45], v[48:49]
	v_pk_mul_f32 v[46:47], v[46:47], v[50:51]
	v_pk_mul_f32 v[36:37], v[36:37], v[40:41]
	v_pk_mul_f32 v[38:39], v[38:39], v[42:43]
	v_cvt_pk_bf16_f32 v44, v44, v45
	v_cvt_pk_bf16_f32 v46, v46, v47
	v_cvt_pk_bf16_f32 v36, v36, v37
	v_cvt_pk_bf16_f32 v38, v38, v39
	global_store_short v192, v44, s[30:31]
	global_store_short_d16_hi v193, v44, s[30:31] offset:1536
	global_store_short v194, v46, s[30:31] offset:3072
	global_store_short_d16_hi v195, v46, s[30:31] offset:512
	global_store_short v192, v36, s[30:31] offset:128
	global_store_short_d16_hi v193, v36, s[30:31] offset:1664
	global_store_short v194, v38, s[30:31] offset:3200
	global_store_short_d16_hi v195, v38, s[30:31] offset:640
	s_waitcnt lgkmcnt(1)
; DI float fexp2(float x) { return __builtin_amdgcn_exp2f(x); }
;     ...
;       for (int m = 0; m < 4; ++m) {
;         const int rowb = ai * 128 + wr * 64 + m * 16 + fq * 4;
;         const f32x4 rs4 = *(const f32x4*)(rstdL + rowb);
; #pragma unroll
;         for (int bj = 0; bj < 2; ++bj) {
;           bf16_t* op = e.out + (size_t)(m0 + rowb) * e.ldo + ((n0 + bj * 128 + wc * 32) >> 1) + fr;
; #pragma unroll
;           for (int j = 0; j < 4; ++j) {
;             const float g = acc[ai][bj][m][0][j] * rs4[j], u = acc[ai][bj][m][1][j] * rs4[j];
;             const float rv = g * __builtin_amdgcn_rcpf(1.f + fexp2(-g * LOG2E)) * u;
;             op[(size_t)j * e.ldo] = (bf16_t)(pack2(rv, 0.f) & 0xffffu);
;           }
;         }
;       }
;     __syncthreads();
;     return;
	v_pk_mul_f32 v[32:33], v[32:33], v[174:175]
	v_pk_mul_f32 v[34:35], v[34:35], v[176:177]
	v_pk_mul_f32 v[24:25], v[24:25], v[174:175]
	v_pk_mul_f32 v[26:27], v[26:27], v[176:177]
	v_pk_mul_f32 v[182:183], v[32:33], s[12:13] op_sel_hi:[1,0]
	v_pk_mul_f32 v[184:185], v[34:35], s[12:13] op_sel_hi:[1,0]
	v_pk_mul_f32 v[186:187], v[24:25], s[12:13] op_sel_hi:[1,0]
	v_pk_mul_f32 v[188:189], v[26:27], s[12:13] op_sel_hi:[1,0]
	v_exp_f32_e32 v182, v182
	v_exp_f32_e32 v183, v183
	v_exp_f32_e32 v184, v184
	v_exp_f32_e32 v185, v185
	v_exp_f32_e32 v186, v186
	v_exp_f32_e32 v187, v187
	v_exp_f32_e32 v188, v188
	v_exp_f32_e32 v189, v189
	v_add_u32_e32 v192, 0xdc000, v190
	v_add_u32_e32 v193, 0x1000, v192
	v_add_u32_e32 v194, 0x2000, v192
	v_add_u32_e32 v195, 0x4000, v192
	v_pk_add_f32 v[182:183], v[182:183], 1.0 op_sel_hi:[1,0]
	v_pk_add_f32 v[184:185], v[184:185], 1.0 op_sel_hi:[1,0]
	v_pk_add_f32 v[186:187], v[186:187], 1.0 op_sel_hi:[1,0]
	v_pk_add_f32 v[188:189], v[188:189], 1.0 op_sel_hi:[1,0]
	v_rcp_f32_e32 v182, v182
	v_rcp_f32_e32 v183, v183
	v_rcp_f32_e32 v184, v184
	v_rcp_f32_e32 v185, v185
	v_rcp_f32_e32 v186, v186
	v_rcp_f32_e32 v187, v187
	v_rcp_f32_e32 v188, v188
	v_rcp_f32_e32 v189, v189
	v_pk_mul_f32 v[28:29], v[28:29], v[174:175]
	v_pk_mul_f32 v[30:31], v[30:31], v[176:177]
	v_pk_mul_f32 v[20:21], v[20:21], v[174:175]
	v_pk_mul_f32 v[22:23], v[22:23], v[176:177]
	v_pk_mul_f32 v[32:33], v[32:33], v[182:183]
	v_pk_mul_f32 v[34:35], v[34:35], v[184:185]
	v_pk_mul_f32 v[24:25], v[24:25], v[186:187]
	v_pk_mul_f32 v[26:27], v[26:27], v[188:189]
	v_pk_mul_f32 v[28:29], v[28:29], v[32:33]
	v_pk_mul_f32 v[30:31], v[30:31], v[34:35]
	v_pk_mul_f32 v[20:21], v[20:21], v[24:25]
	v_pk_mul_f32 v[22:23], v[22:23], v[26:27]
	v_cvt_pk_bf16_f32 v28, v28, v29
	v_cvt_pk_bf16_f32 v30, v30, v31
	v_cvt_pk_bf16_f32 v20, v20, v21
	v_cvt_pk_bf16_f32 v22, v22, v23
	global_store_short v192, v28, s[30:31]
	global_store_short_d16_hi v193, v28, s[30:31] offset:1536
	global_store_short v194, v30, s[30:31] offset:3072
	global_store_short_d16_hi v195, v30, s[30:31] offset:512
	global_store_short v192, v20, s[30:31] offset:128
	global_store_short_d16_hi v193, v20, s[30:31] offset:1664
	global_store_short v194, v22, s[30:31] offset:3200
	global_store_short_d16_hi v195, v22, s[30:31] offset:640
	s_waitcnt lgkmcnt(0)
	v_pk_mul_f32 v[16:17], v[16:17], v[178:179]
	v_pk_mul_f32 v[18:19], v[18:19], v[180:181]
	v_pk_mul_f32 v[8:9], v[8:9], v[178:179]
	v_pk_mul_f32 v[10:11], v[10:11], v[180:181]
	v_pk_mul_f32 v[182:183], v[16:17], s[12:13] op_sel_hi:[1,0]
	v_pk_mul_f32 v[184:185], v[18:19], s[12:13] op_sel_hi:[1,0]
	v_pk_mul_f32 v[186:187], v[8:9], s[12:13] op_sel_hi:[1,0]
	v_pk_mul_f32 v[188:189], v[10:11], s[12:13] op_sel_hi:[1,0]
	v_exp_f32_e32 v182, v182
	v_exp_f32_e32 v183, v183
	v_exp_f32_e32 v184, v184
	v_exp_f32_e32 v185, v185
	v_exp_f32_e32 v186, v186
	v_exp_f32_e32 v187, v187
	v_exp_f32_e32 v188, v188
	v_exp_f32_e32 v189, v189
	v_add_u32_e32 v192, 0xf2000, v190
	v_add_u32_e32 v193, 0x1000, v192
	v_add_u32_e32 v194, 0x2000, v192
	v_add_u32_e32 v195, 0x4000, v192
	v_pk_add_f32 v[182:183], v[182:183], 1.0 op_sel_hi:[1,0]
	v_pk_add_f32 v[184:185], v[184:185], 1.0 op_sel_hi:[1,0]
	v_pk_add_f32 v[186:187], v[186:187], 1.0 op_sel_hi:[1,0]
	v_pk_add_f32 v[188:189], v[188:189], 1.0 op_sel_hi:[1,0]
	v_rcp_f32_e32 v182, v182
	v_rcp_f32_e32 v183, v183
	v_rcp_f32_e32 v184, v184
	v_rcp_f32_e32 v185, v185
	v_rcp_f32_e32 v186, v186
	v_rcp_f32_e32 v187, v187
	v_rcp_f32_e32 v188, v188
	v_rcp_f32_e32 v189, v189
	v_pk_mul_f32 v[12:13], v[12:13], v[178:179]
	v_pk_mul_f32 v[14:15], v[14:15], v[180:181]
	v_pk_mul_f32 v[4:5], v[4:5], v[178:179]
	v_pk_mul_f32 v[6:7], v[6:7], v[180:181]
	v_pk_mul_f32 v[16:17], v[16:17], v[182:183]
	v_pk_mul_f32 v[18:19], v[18:19], v[184:185]
	v_pk_mul_f32 v[8:9], v[8:9], v[186:187]
	v_pk_mul_f32 v[10:11], v[10:11], v[188:189]
	v_pk_mul_f32 v[12:13], v[12:13], v[16:17]
	v_pk_mul_f32 v[14:15], v[14:15], v[18:19]
	v_pk_mul_f32 v[4:5], v[4:5], v[8:9]
	v_pk_mul_f32 v[6:7], v[6:7], v[10:11]
	v_cvt_pk_bf16_f32 v12, v12, v13
	v_cvt_pk_bf16_f32 v14, v14, v15
	v_cvt_pk_bf16_f32 v4, v4, v5
	v_cvt_pk_bf16_f32 v6, v6, v7
	global_store_short v192, v12, s[30:31]
	global_store_short_d16_hi v193, v12, s[30:31] offset:1536
	global_store_short v194, v14, s[30:31] offset:3072
	global_store_short_d16_hi v195, v14, s[30:31] offset:512
	global_store_short v192, v4, s[30:31] offset:128
	global_store_short_d16_hi v193, v4, s[30:31] offset:1664
	global_store_short v194, v6, s[30:31] offset:3200
	global_store_short_d16_hi v195, v6, s[30:31] offset:640
	s_waitcnt vmcnt(63) expcnt(7) lgkmcnt(15)
	s_barrier
